# attention unit prologue: 32-lane max of the window bound taken with DPP maxes + one v_permlane16_swap instead of five dependent ds_bpermute round trips
# speedup vs baseline: 1.0106x; 1.0100x over previous
; __device__ __forceinline__ void attn_unit(const bf16* __restrict__ P, bf16* __restrict__ MIXIN, const float* __restrict__ gn, int seq0, int h, int q0, int nt, float kmax0, float kmax1, float slope, float lam, char* lds) {
;   int tid_ = threadIdx.x; asm volatile("" : "+v"(tid_)); const int tid = tid_, wid = tid >> 6, lane = tid & 63, r32 = lane & 31, hi = lane >> 5, mp = wid >> 2, wq = wid & 3;
;   char* V_lds = lds; char* K_lds = lds + 2 * SHM_V;
;   float* ws = (float*)(lds + 2 * SHM_V + 2 * SHM_K) + wid * 64; float* li_l = ws; float* al_l = ws + 32;
;   float l_reg = 0; f32x16 o[4] = {}; bf16x8 qr[4];
;   const int qpos = q0 + wq * 32 + r32;
;   const bf16* Qw = P + (size_t)(seq0 + qpos) * LDP + C_DAQ + h * 128 + mp * 64 + hi * 8;
; #pragma unroll
;   for (int d0 = 0; d0 < 4; ++d0) qr[d0] = *reinterpret_cast<const bf16x8*>(Qw + d0 * 16);
;   const bf16* Kh = P + (size_t)seq0 * LDP + C_DAK + h * 128;
;   int t0, t1; float m_reg;
;   { const bf16* Kw = Kh + (size_t)qpos * LDP + mp * 64 + hi * 8; float qn = 0.f, sd = 0.f;
; #pragma unroll
;     for (int d0 = 0; d0 < 4; ++d0) { const bf16x8 kf = *reinterpret_cast<const bf16x8*>(Kw + d0 * 16);
; #pragma unroll
;       for (int e = 0; e < 8; ++e) { const float qv = bf2f((unsigned short)qr[d0][e]), kv = bf2f((unsigned short)kf[e]); qn += qv * qv; sd += qv * kv; } }
; __global__ void __launch_bounds__(NWAVES * 64, 2) hymba_fwd(Args args) {
;     ...
;             const float kmax0 = sqrtf(__uint_as_float(__hip_atomic_load(ctl + CW_NORM + sq * 16 + 8 + h * 2 + 0, __ATOMIC_RELAXED, __HIP_MEMORY_SCOPE_AGENT)));
;             const float kmax1 = sqrtf(__uint_as_float(__hip_atomic_load(ctl + CW_NORM + sq * 16 + 8 + h * 2 + 1, __ATOMIC_RELAXED, __HIP_MEMORY_SCOPE_AGENT)));
.LBB0_307:
	s_sub_i32 s85, 3, s24
	s_lshl_b64 s[0:1], s[0:1], 2
	s_add_u32 s6, s70, s0
	s_addc_u32 s7, s71, s1
	s_lshl_b32 s10, s85, 1
	s_lshl_b64 s[0:1], s[10:11], 2
	s_add_u32 s0, s6, s0
	s_addc_u32 s1, s7, s1
	global_load_dword v22, v177, s[0:1] offset:544 sc1
	global_load_dword v23, v177, s[0:1] offset:548 sc1
	v_mov_b32_e32 v229, v210
	s_mul_i32 s0, s35, 0xd00
	v_ashrrev_i32_e32 v21, 6, v229
	v_lshlrev_b32_e32 v0, 5, v21
	v_and_b32_e32 v36, 31, v229
	v_and_b32_e32 v0, 0x60, v0
	s_mov_b32 s1, s11
	v_or3_b32 v20, s31, v0, v36
	s_lshl_b32 s10, s85, 8
	s_lshl_b64 s[0:1], s[0:1], 1
	v_add_u32_e32 v0, s35, v20
	s_add_u32 s0, s44, s0
	v_mul_i32_i24_e32 v176, 0xd00, v0
	v_ashrrev_i32_e32 v0, 2, v229
	s_addc_u32 s1, s45, s1
	v_and_b32_e32 v32, 0xffffffc0, v0
	s_add_u32 s24, s0, s10
	v_ashrrev_i32_e32 v33, 31, v32
	s_addc_u32 s25, s1, 0
	v_mul_u32_u24_e32 v0, 0xd00, v20
	v_mov_b32_e32 v1, v177
	v_bfe_u32 v19, v229, 5, 1
	v_lshlrev_b64 v[8:9], 1, v[32:33]
	v_lshl_add_u64 v[0:1], v[0:1], 1, s[24:25]
	v_lshl_add_u64 v[2:3], v[176:177], 1, s[44:45]
	v_lshlrev_b32_e32 v176, 4, v19
	v_lshl_add_u64 v[0:1], v[0:1], 0, v[8:9]
	v_lshl_add_u64 v[0:1], v[0:1], 0, v[176:177]
	global_load_dwordx4 v[4:7], v[0:1], off offset:1024
	v_lshl_add_u64 v[2:3], v[2:3], 0, s[10:11]
	v_lshl_add_u64 v[2:3], v[2:3], 0, v[8:9]
	v_lshl_add_u64 v[16:17], v[2:3], 0, v[176:177]
	global_load_dwordx4 v[132:135], v[16:17], off
	global_load_dwordx4 v[128:131], v[16:17], off offset:32
	global_load_dwordx4 v[8:11], v[0:1], off offset:1056
	global_load_dwordx4 v[12:15], v[0:1], off offset:1088
	s_nop 0
	global_load_dwordx4 v[0:3], v[0:1], off offset:1120
	s_nop 0
	global_load_dwordx4 v[140:143], v[16:17], off offset:64
	global_load_dwordx4 v[136:139], v[16:17], off offset:96
	s_waitcnt vmcnt(9)
	v_mul_f32_e32 v24, 0x4f800000, v22
	v_cmp_gt_f32_e32 vcc, s26, v22
	s_waitcnt vmcnt(8)
	v_mul_f32_e32 v25, 0x4f800000, v23
	v_cmp_gt_f32_e64 s[0:1], s26, v23
	v_cndmask_b32_e32 v24, v22, v24, vcc
	s_waitcnt vmcnt(6)
	v_and_b32_e32 v33, 0xffff0000, v133
	v_cndmask_b32_e64 v22, v23, v25, s[0:1]
	v_sqrt_f32_e32 v23, v24
	v_sqrt_f32_e32 v25, v22
	v_lshlrev_b32_e32 v34, 16, v134
	v_and_b32_e32 v35, 0xffff0000, v134
	v_add_u32_e32 v16, -1, v23
	v_add_u32_e32 v26, -1, v25
	v_fma_f32 v28, -v16, v23, v24
	v_add_u32_e32 v17, 1, v23
	v_fma_f32 v30, -v26, v25, v22
	v_cmp_ge_f32_e64 s[6:7], 0, v28
	v_add_u32_e32 v27, 1, v25
	v_fma_f32 v29, -v17, v23, v24
	v_cndmask_b32_e64 v16, v23, v16, s[6:7]
	v_cmp_ge_f32_e64 s[6:7], 0, v30
	v_fma_f32 v31, -v27, v25, v22
	v_and_b32_e32 v30, 0xffff0000, v132
	v_cndmask_b32_e64 v23, v25, v26, s[6:7]
	v_cmp_lt_f32_e64 s[6:7], 0, v29
	v_lshlrev_b32_e32 v26, 16, v5
	v_and_b32_e32 v25, 0xffff0000, v4
	v_cndmask_b32_e64 v16, v16, v17, s[6:7]
	v_cmp_lt_f32_e64 s[6:7], 0, v31
	v_lshlrev_b32_e32 v28, 16, v6
	v_and_b32_e32 v29, 0xffff0000, v6
	v_cndmask_b32_e64 v17, v23, v27, s[6:7]
	v_and_b32_e32 v27, 0xffff0000, v5
	v_mul_f32_e32 v5, 0x37800000, v17
	v_lshlrev_b32_e32 v23, 16, v4
	v_mul_f32_e32 v4, 0x37800000, v16
	v_cndmask_b32_e64 v5, v17, v5, s[0:1]
	v_lshlrev_b32_e32 v17, 16, v132
	v_cndmask_b32_e32 v4, v16, v4, vcc
	v_fma_f32 v6, v17, v23, 0
	v_mul_f32_e32 v16, v30, v30
	v_lshlrev_b32_e32 v31, 16, v133
	v_fmac_f32_e32 v16, v17, v17
	v_fmac_f32_e32 v6, v30, v25
	v_fmac_f32_e32 v16, v31, v31
	v_fmac_f32_e32 v6, v31, v26
	v_fmac_f32_e32 v16, v33, v33
	v_fmac_f32_e32 v6, v33, v27
	v_fmac_f32_e32 v16, v34, v34
	v_fmac_f32_e32 v6, v34, v28
	v_fmac_f32_e32 v16, v35, v35
	v_fmac_f32_e32 v6, v35, v29
	v_lshlrev_b32_e32 v17, 16, v135
	v_lshlrev_b32_e32 v23, 16, v7
	v_fmac_f32_e32 v16, v17, v17
	v_fmac_f32_e32 v6, v17, v23
	v_and_b32_e32 v17, 0xffff0000, v135
	v_and_b32_e32 v7, 0xffff0000, v7
	v_fmac_f32_e32 v16, v17, v17
	v_fmac_f32_e32 v6, v17, v7
	s_waitcnt vmcnt(5)
	v_lshlrev_b32_e32 v7, 16, v128
	s_waitcnt vmcnt(4)
	v_lshlrev_b32_e32 v17, 16, v8
	v_fmac_f32_e32 v16, v7, v7
	v_fmac_f32_e32 v6, v7, v17
	v_and_b32_e32 v7, 0xffff0000, v128
	v_and_b32_e32 v8, 0xffff0000, v8
	v_fmac_f32_e32 v16, v7, v7
	v_fmac_f32_e32 v6, v7, v8
	v_lshlrev_b32_e32 v7, 16, v129
	v_lshlrev_b32_e32 v8, 16, v9
	v_fmac_f32_e32 v16, v7, v7
	v_fmac_f32_e32 v6, v7, v8
	v_and_b32_e32 v7, 0xffff0000, v129
	v_and_b32_e32 v8, 0xffff0000, v9
	v_fmac_f32_e32 v16, v7, v7
	v_fmac_f32_e32 v6, v7, v8
	v_lshlrev_b32_e32 v7, 16, v130
	v_lshlrev_b32_e32 v8, 16, v10
	v_fmac_f32_e32 v16, v7, v7
	v_fmac_f32_e32 v6, v7, v8
	v_and_b32_e32 v7, 0xffff0000, v130
	v_and_b32_e32 v8, 0xffff0000, v10
	v_fmac_f32_e32 v16, v7, v7
	v_fmac_f32_e32 v6, v7, v8
	v_lshlrev_b32_e32 v7, 16, v131
	v_lshlrev_b32_e32 v8, 16, v11
	v_fmac_f32_e32 v16, v7, v7
	v_fmac_f32_e32 v6, v7, v8
	v_and_b32_e32 v7, 0xffff0000, v131
	v_and_b32_e32 v8, 0xffff0000, v11
	v_fmac_f32_e32 v16, v7, v7
	v_fmac_f32_e32 v6, v7, v8
	s_waitcnt vmcnt(1)
; __device__ __forceinline__ void attn_unit(const bf16* __restrict__ P, bf16* __restrict__ MIXIN, const float* __restrict__ gn, int seq0, int h, int q0, int nt, float kmax0, float kmax1, float slope, float lam, char* lds) {
;     ...
;       for (int e = 0; e < 8; ++e) { const float qv = bf2f((unsigned short)qr[d0][e]), kv = bf2f((unsigned short)kf[e]); qn += qv * qv; sd += qv * kv; } }
;     qn += __shfl_xor(qn, 32); sd += __shfl_xor(sd, 32);
;     const float ub = sqrtf(qn) * (mp ? kmax1 : kmax0) * 1.0001f;
;     m_reg = fminf(ub, sd + 60.f);
;     float bnd = ub - sd;
;     bnd = fmaxf(bnd, __shfl_xor(bnd, 1)); bnd = fmaxf(bnd, __shfl_xor(bnd, 2)); bnd = fmaxf(bnd, __shfl_xor(bnd, 4)); bnd = fmaxf(bnd, __shfl_xor(bnd, 8)); bnd = fmaxf(bnd, __shfl_xor(bnd, 16));
;     float* wsb = (float*)(lds + 2 * SHM_V + 2 * SHM_K);
;     if (lane == 0) wsb[wid] = bnd;
	v_lshlrev_b32_e32 v7, 16, v140
	v_lshlrev_b32_e32 v8, 16, v12
	v_fmac_f32_e32 v16, v7, v7
	v_fmac_f32_e32 v6, v7, v8
	v_and_b32_e32 v7, 0xffff0000, v140
	v_and_b32_e32 v8, 0xffff0000, v12
	v_fmac_f32_e32 v16, v7, v7
	v_fmac_f32_e32 v6, v7, v8
	v_lshlrev_b32_e32 v7, 16, v141
	v_lshlrev_b32_e32 v8, 16, v13
	v_fmac_f32_e32 v16, v7, v7
	v_fmac_f32_e32 v6, v7, v8
	v_and_b32_e32 v7, 0xffff0000, v141
	v_and_b32_e32 v8, 0xffff0000, v13
	v_fmac_f32_e32 v16, v7, v7
	v_fmac_f32_e32 v6, v7, v8
	v_lshlrev_b32_e32 v7, 16, v142
	v_lshlrev_b32_e32 v8, 16, v14
	v_fmac_f32_e32 v16, v7, v7
	v_fmac_f32_e32 v6, v7, v8
	v_and_b32_e32 v7, 0xffff0000, v142
	v_and_b32_e32 v8, 0xffff0000, v14
	v_fmac_f32_e32 v16, v7, v7
	v_fmac_f32_e32 v6, v7, v8
	v_lshlrev_b32_e32 v7, 16, v143
	v_lshlrev_b32_e32 v8, 16, v15
	v_fmac_f32_e32 v16, v7, v7
	v_fmac_f32_e32 v6, v7, v8
	v_and_b32_e32 v7, 0xffff0000, v143
	v_and_b32_e32 v8, 0xffff0000, v15
	v_fmac_f32_e32 v16, v7, v7
	v_fmac_f32_e32 v6, v7, v8
	s_waitcnt vmcnt(0)
	v_lshlrev_b32_e32 v7, 16, v136
	v_lshlrev_b32_e32 v8, 16, v0
	v_fmac_f32_e32 v16, v7, v7
	v_fmac_f32_e32 v6, v7, v8
	v_and_b32_e32 v7, 0xffff0000, v136
	v_and_b32_e32 v0, 0xffff0000, v0
	v_fmac_f32_e32 v16, v7, v7
	v_fmac_f32_e32 v6, v7, v0
	v_lshlrev_b32_e32 v0, 16, v137
	v_lshlrev_b32_e32 v7, 16, v1
	v_fmac_f32_e32 v16, v0, v0
	v_fmac_f32_e32 v6, v0, v7
	v_and_b32_e32 v0, 0xffff0000, v137
	v_and_b32_e32 v1, 0xffff0000, v1
	v_fmac_f32_e32 v16, v0, v0
	v_fmac_f32_e32 v6, v0, v1
	v_lshlrev_b32_e32 v0, 16, v138
	v_lshlrev_b32_e32 v1, 16, v2
	v_cmp_class_f32_e32 vcc, v24, v220
	v_fmac_f32_e32 v16, v0, v0
	v_fmac_f32_e32 v6, v0, v1
	v_and_b32_e32 v0, 0xffff0000, v138
	v_and_b32_e32 v1, 0xffff0000, v2
	v_cndmask_b32_e32 v4, v4, v24, vcc
	v_fmac_f32_e32 v16, v0, v0
	v_fmac_f32_e32 v6, v0, v1
	v_lshlrev_b32_e32 v0, 16, v139
	v_cmp_lt_i32_e32 vcc, v214, v213
	v_fmac_f32_e32 v16, v0, v0
	v_and_b32_e32 v1, 0xffff0000, v139
	v_cndmask_b32_e32 v2, v211, v214, vcc
	v_fmac_f32_e32 v16, v1, v1
	v_lshlrev_b32_e32 v2, 2, v2
	ds_bpermute_b32 v7, v2, v16
	v_lshlrev_b32_e32 v8, 16, v3
	v_fmac_f32_e32 v6, v0, v8
	v_and_b32_e32 v0, 0xffff0000, v3
	v_fmac_f32_e32 v6, v1, v0
	s_waitcnt lgkmcnt(0)
	v_add_f32_e32 v0, v16, v7
	ds_bpermute_b32 v1, v2, v6
	v_mul_f32_e32 v2, 0x4f800000, v0
	v_cmp_gt_f32_e32 vcc, s26, v0
	v_cmp_class_f32_e64 s[0:1], v22, v220
	v_and_b32_e32 v33, 63, v229
	v_cndmask_b32_e32 v2, v0, v2, vcc
	v_sqrt_f32_e32 v3, v2
	s_waitcnt lgkmcnt(0)
	v_add_f32_e32 v0, v6, v1
	v_cndmask_b32_e64 v5, v5, v22, s[0:1]
	v_add_u32_e32 v1, -1, v3
	v_fma_f32 v6, -v1, v3, v2
	v_cmp_ge_f32_e64 s[0:1], 0, v6
	v_add_u32_e32 v6, 1, v3
	s_nop 0
	v_cndmask_b32_e64 v1, v3, v1, s[0:1]
	v_fma_f32 v3, -v6, v3, v2
	v_cmp_lt_f32_e64 s[0:1], 0, v3
	s_nop 1
	v_cndmask_b32_e64 v1, v1, v6, s[0:1]
	v_mul_f32_e32 v3, 0x37800000, v1
	v_cndmask_b32_e32 v1, v1, v3, vcc
	v_cmp_class_f32_e32 vcc, v2, v220
	s_mov_b32 s0, 0x3f800347
	s_nop 0
	v_cndmask_b32_e32 v1, v1, v2, vcc
	v_cmp_gt_u32_e32 vcc, s28, v229
	s_nop 1
	v_cndmask_b32_e32 v2, v5, v4, vcc
	v_cmp_lt_i32_e32 vcc, v252, v213
	v_mul_f32_e32 v1, v2, v1
	v_fma_f32 v2, v1, s0, -v0
	v_cndmask_b32_e32 v3, v211, v252, vcc
	v_lshlrev_b32_e32 v228, 2, v3
	v_cmp_lt_i32_e32 vcc, v253, v213
	s_nop 1
	v_max_f32_dpp v2, v2, v2 quad_perm:[1,0,3,2] row_mask:0xf bank_mask:0xf
	v_cndmask_b32_e32 v3, v211, v253, vcc
	v_lshlrev_b32_e32 v227, 2, v3
	v_cmp_lt_i32_e32 vcc, v254, v213
	s_nop 1
	v_max_f32_dpp v2, v2, v2 quad_perm:[2,3,0,1] row_mask:0xf bank_mask:0xf
	v_cndmask_b32_e32 v3, v211, v254, vcc
	v_lshlrev_b32_e32 v226, 2, v3
	v_cmp_lt_i32_e32 vcc, v212, v213
	s_nop 1
	v_max_f32_dpp v2, v2, v2 row_half_mirror row_mask:0xf bank_mask:0xf
	v_cndmask_b32_e32 v3, v211, v212, vcc
	v_lshlrev_b32_e32 v225, 2, v3
	v_cmp_lt_i32_e32 vcc, v218, v213
	s_nop 1
	v_max_f32_dpp v2, v2, v2 row_mirror row_mask:0xf bank_mask:0xf
	v_cndmask_b32_e32 v3, v211, v218, vcc
	v_lshlrev_b32_e32 v224, 2, v3
	v_mov_b32_e32 v3, v2
	s_nop 1
	v_permlane16_swap_b32_e32 v2, v3
	s_nop 0
	v_cmp_eq_u32_e32 vcc, 0, v33
	s_and_saveexec_b64 s[0:1], vcc
	s_cbranch_execz .LBB0_309
	s_waitcnt lgkmcnt(0)
	v_max_f32_e32 v3, v3, v3
	v_max_f32_e32 v2, v2, v2
	v_max_f32_e32 v2, v2, v3
	v_lshl_add_u32 v3, v21, 2, 0
	v_add_u32_e32 v3, 0x10000, v3
	ds_write_b32 v3, v2
